# attention window lookahead with the probe loads issued right after the drain (earlier than before)
# speedup vs baseline: 1.0036x; 1.0036x over previous
; __device__ __forceinline__ int crow(int r,int hi){return (r&3)+8*(r>>2)+4*hi;}
; template<int THRL> __device__ __forceinline__ void attn_unit(int b,int h,int qb,int t0,float cqv,float mfix,const float*__restrict__ cf,float cref,unsigned*counter,const bf16*Q,const bf16*__restrict__ K,const bf16*__restrict__ V,bf16*O,const bf16*__restrict__ G,char*shm){
;     ...
;   int unext_=0; if(tid==0) unext_=(int)atomicAdd(counter,1u);
;   {auto rr=__builtin_amdgcn_permlane32_swap(__float_as_uint(l_reg),__float_as_uint(l_reg),false,false);l_reg=__uint_as_float(rr[0])+__uint_as_float(rr[1]);}
;   if(hi==0)wsf[32+r32]=l_reg;asm volatile("s_waitcnt lgkmcnt(0)":::"memory");
;   float rli[16];
;   #pragma unroll
;   for(int r=0;r<16;++r)rli[r]=__builtin_amdgcn_rcpf(wsf[32+crow(r,hi)]);
;   bf16*Ow=O+(rowbase+q0+wid*QBLK)*DM+h*D;
;   { bf16*stg=(bf16*)(shm+LDS_OST)+wid*2048;
;     #pragma unroll
;     for(int r=0;r<16;++r){const int orow=crow(r,hi);
;       #pragma unroll
;       for(int d0=0;d0<2;++d0)stg[orow*64+d0*32+r32]=__float2bfloat16(o[d0][r]*rli[r]);}
;     asm volatile("s_waitcnt lgkmcnt(0)":::"memory");
;     const bf16*Gw=G+(rowbase+q0+wid*QBLK)*DM+h*D;
;     u32x4 gv4[4];
;     #pragma unroll
;     for(int i=0;i<4;++i)gv4[i]=*(const u32x4*)(Gw+(long)(i*8+(lane>>3))*DM+(lane&7)*8);
.LBB0_874:
	v_cmp_eq_u32_e64 s[100:101], 0, v226
	v_mov_b32_e32 v252, 1
	s_and_saveexec_b64 s[100:101], s[100:101]
	global_atomic_add v252, v205, v252, s[10:11] offset:256 sc0
	s_mov_b64 exec, s[100:101]
	s_lshl_b64 s[98:99], s[38:39], 1
	v_lshlrev_b32_e32 v196, 1, v225
	v_lshlrev_b32_e32 v197, 8, v224
	s_add_u32 s98, s2, s98
	s_addc_u32 s99, s3, s99
	v_and_b32_e32 v196, 0x70, v196
	v_and_b32_e32 v197, 0x3800, v197
	s_add_u32 s98, s98, s52
	s_addc_u32 s99, s99, s53
	v_add_u32_e32 v196, v196, v197
	v_add_u32_e32 v197, 0x4000, v196
	v_add_u32_e32 v198, 0x8000, v196
	v_add_u32_e32 v199, 0xc000, v196
	global_load_dwordx4 v[180:183], v196, s[98:99]
	global_load_dwordx4 v[184:187], v197, s[98:99]
	global_load_dwordx4 v[188:191], v198, s[98:99]
	global_load_dwordx4 v[192:195], v199, s[98:99]
	s_cmp_lg_u32 0, -1
	s_cselect_b32 s4, 0, 0
	s_addk_i32 s4, 0x6000
	v_add3_u32 v33, v234, s4, v232
	v_add_u32_e32 v38, s72, v235
	ds_read_b64_tr_b16 v[176:177], v38 offset:24576
	ds_read_b64_tr_b16 v[178:179], v38 offset:25088
	v_add_f32_e32 v34, v64, v65
	v_add_f32_e32 v34, v66, v34
	v_add_f32_e32 v34, v67, v34
	v_add_f32_e32 v34, v68, v34
	v_add_f32_e32 v34, v69, v34
	v_cvt_pk_bf16_f32 v128, v64, v65
	v_cvt_pk_bf16_f32 v129, v66, v67
	s_waitcnt lgkmcnt(3)
	v_mfma_f32_32x32x16_bf16 v[96:111], v[172:175], v[124:127], 0
	ds_read_b64_tr_b16 v[172:173], v38 offset:28672
	ds_read_b64_tr_b16 v[174:175], v38 offset:29184
	v_add_f32_e32 v34, v70, v34
	v_add_f32_e32 v34, v71, v34
	v_add_f32_e32 v34, v72, v34
	v_add_f32_e32 v39, v73, v34
	v_cvt_pk_bf16_f32 v130, v68, v69
	v_cvt_pk_bf16_f32 v131, v70, v71
	s_waitcnt lgkmcnt(4)
	v_mfma_f32_32x32x16_bf16 v[80:95], v[164:167], v[124:127], 0
	ds_read_b64_tr_b16 v[34:35], v38 offset:25600
	ds_read_b64_tr_b16 v[36:37], v38 offset:26112
	v_add_f32_e32 v39, v74, v39
	v_add_f32_e32 v39, v75, v39
	v_add_f32_e32 v39, v76, v39
	v_add_f32_e32 v39, v77, v39
	v_cvt_pk_bf16_f32 v136, v72, v73
	v_cvt_pk_bf16_f32 v137, v74, v75
	v_mfma_f32_32x32x16_bf16 v[96:111], v[168:171], v[120:123], v[96:111]
	ds_read_b64_tr_b16 v[70:71], v38 offset:29696
	ds_read_b64_tr_b16 v[72:73], v38 offset:30208
	v_add_f32_e32 v39, v78, v39
	v_add_f32_e32 v39, v79, v39
	v_add_f32_e32 v39, v48, v39
	v_add_f32_e32 v39, v49, v39
	v_cvt_pk_bf16_f32 v138, v76, v77
	v_cvt_pk_bf16_f32 v139, v78, v79
	v_mfma_f32_32x32x16_bf16 v[80:95], v[160:163], v[120:123], v[80:95]
	ds_read_b64_tr_b16 v[120:121], v38 offset:26624
	ds_read_b64_tr_b16 v[122:123], v38 offset:27136
	v_add_f32_e32 v39, v50, v39
	v_add_f32_e32 v39, v51, v39
	v_add_f32_e32 v39, v52, v39
	v_add_f32_e32 v39, v53, v39
	v_cvt_pk_bf16_f32 v132, v48, v49
	v_cvt_pk_bf16_f32 v133, v50, v51
	v_mfma_f32_32x32x16_bf16 v[96:111], v[156:159], v[116:119], v[96:111]
	ds_read_b64_tr_b16 v[66:67], v38 offset:30720
	ds_read_b64_tr_b16 v[68:69], v38 offset:31232
	v_add_f32_e32 v39, v54, v39
	v_add_f32_e32 v39, v55, v39
	v_add_f32_e32 v39, v56, v39
	v_add_f32_e32 v39, v57, v39
	v_cvt_pk_bf16_f32 v134, v52, v53
	v_cvt_pk_bf16_f32 v135, v54, v55
	v_mfma_f32_32x32x16_bf16 v[80:95], v[152:155], v[116:119], v[80:95]
	ds_read_b64_tr_b16 v[74:75], v38 offset:27648
	ds_read_b64_tr_b16 v[76:77], v38 offset:28160
	v_add_f32_e32 v39, v58, v39
	v_add_f32_e32 v39, v59, v39
	v_add_f32_e32 v39, v60, v39
	v_add_f32_e32 v39, v61, v39
	v_cvt_pk_bf16_f32 v140, v56, v57
	v_cvt_pk_bf16_f32 v141, v58, v59
	v_mfma_f32_32x32x16_bf16 v[96:111], v[148:151], v[112:115], v[96:111]
	ds_read_b64_tr_b16 v[116:117], v38 offset:31744
	ds_read_b64_tr_b16 v[118:119], v38 offset:32256
	v_add_f32_e32 v38, v62, v39
	v_add_f32_e32 v38, v63, v38
	v_add_f32_e32 v78, 0, v38
	v_cvt_pk_bf16_f32 v142, v60, v61
	v_cvt_pk_bf16_f32 v143, v62, v63
	v_mfma_f32_32x32x16_bf16 v[80:95], v[144:147], v[112:115], v[80:95]
	s_lshl_b32 s4, s67, 2
	s_add_i32 s4, s4, 0
	s_add_i32 s4, s4, 0x14800
	v_add_u32_e32 v38, s4, v230
	v_add_u32_e32 v79, 0xffffff00, v38
	ds_read_b128 v[38:41], v79
	ds_read_b128 v[42:45], v79 offset:32
	ds_read_b128 v[46:49], v79 offset:64
	ds_read_b128 v[50:53], v79 offset:96
	ds_read_b128 v[54:57], v79 offset:128
	ds_read_b128 v[58:61], v79 offset:160
	ds_read_b128 v[62:65], v79 offset:192
	ds_read_b128 v[112:115], v79 offset:224
	s_waitcnt lgkmcnt(7)
	v_sub_f32_e32 v39, v206, v39
	s_waitcnt lgkmcnt(3)
	v_sub_f32_e32 v55, v206, v55
	v_sub_f32_e32 v54, v206, v54
	v_pk_add_f32 v[54:55], v[80:81], v[54:55]
	v_or_b32_e32 v80, 0xe0, v228
	v_sub_f32_e32 v38, v206, v38
	v_or_b32_e32 v79, 0xc0, v228
	v_cmp_le_i32_e32 vcc, v80, v231
	v_pk_add_f32 v[38:39], v[96:97], v[38:39]
	v_sub_f32_e32 v41, v206, v41
	v_cndmask_b32_e32 v80, v223, v54, vcc
	v_cmp_lt_i32_e32 vcc, v79, v231
	v_sub_f32_e32 v40, v206, v40
	s_waitcnt lgkmcnt(2)
	v_sub_f32_e32 v61, v206, v61
	v_cndmask_b32_e32 v81, v223, v39, vcc
	v_cmp_le_i32_e32 vcc, v79, v231
	v_sub_f32_e32 v60, v206, v60
	v_pk_add_f32 v[40:41], v[98:99], v[40:41]
	v_cndmask_b32_e32 v79, v223, v38, vcc
	v_or_b32_e32 v38, 0xe1, v228
	v_cmp_le_i32_e32 vcc, v38, v231
	v_or_b32_e32 v38, 0xc2, v228
	v_sub_f32_e32 v57, v206, v57
	v_sub_f32_e32 v56, v206, v56
	v_pk_add_f32 v[60:61], v[86:87], v[60:61]
	v_cndmask_b32_e32 v86, v223, v55, vcc
	v_cmp_le_i32_e32 vcc, v38, v231
	v_or_b32_e32 v38, 0xe2, v228
	s_waitcnt lgkmcnt(1)
; #define SBAR() __builtin_amdgcn_sched_barrier(0)
; #define WAIT_BAR(N) asm volatile("s_waitcnt vmcnt(" #N ") lgkmcnt(0)\n\ts_barrier":::"memory")
;   #define RESC() do{}while(0)
;   #define ROT() do{sl_prev=sl_cur;sl_cur=sl_next;sl_next=(sl_next==(NSLOT-1)*SLOTB)?0:sl_next+SLOTB;}while(0)
;   #define PKW(P,B) cvtpk_s(P[B],P[B+1])
;   #define ENDW(tt) do{ if((tt)+3<NT){WAIT_BAR(2);} else if((tt)+2<NT){WAIT_BAR(1);} else {WAIT_BAR(0);} }while(0)
; __device__ __forceinline__ void cmask(f32x16&p0,f32x16&p1,int jb,int qrel,int hi){
;   const float NEG=-INFINITY; int kb=64*jb+4*hi;
;   #pragma unroll
;   for(int r=0;r<16;++r){int kv=kb+(r&3)+8*(r>>2); if(kv>qrel)p0[r]=NEG; if(kv+32>qrel)p1[r]=NEG;}
; }
; template<int THRL> __device__ __forceinline__ void attn_unit(int b,int h,int qb,int t0,float cqv,float mfix,const float*__restrict__ cf,float cref,unsigned*counter,const bf16*Q,const bf16*__restrict__ K,const bf16*__restrict__ V,bf16*O,const bf16*__restrict__ G,char*shm){
;     ...
;   int t=1;
;     ...
;   for(;t+5<NT;t+=2){
;     STEP(pB0,pB1,pA0,pA1,t,true,true,true);     WAIT_BAR(2); RESC(); ROT();
;     STEP(pA0,pA1,pB0,pB1,t+1,true,true,true);   WAIT_BAR(2); RESC(); ROT();
;   }
;     ...
;   for(;t+1<NT;t+=2){
;     STEP(pB0,pB1,pA0,pA1,t,(t+3<NT),(t+1<NT),(t+1<NT));       ENDW(t);   RESC(); ROT();
;     STEP(pA0,pA1,pB0,pB1,t+1,(t+4<NT),(t+2<NT),(t+2<NT));     ENDW(t+1); RESC(); ROT();
;   }
;   STEP(pB0,pB1,pA0,pA1,NT-1,false,false,false); RESC();
;   { float sacc=pB0[0]+pB0[1]; _Pragma("unroll") for(int r=2;r<16;++r)sacc+=pB0[r]; _Pragma("unroll") for(int r=0;r<16;++r)sacc+=pB1[r]; l_reg+=sacc;
;     pw0=(u32x4){PKW(pB0,0),PKW(pB0,2),PKW(pB0,4),PKW(pB0,6)};pw1=(u32x4){PKW(pB0,8),PKW(pB0,10),PKW(pB0,12),PKW(pB0,14)};pw2=(u32x4){PKW(pB1,0),PKW(pB1,2),PKW(pB1,4),PKW(pB1,6)};pw3=(u32x4){PKW(pB1,8),PKW(pB1,10),PKW(pB1,12),PKW(pB1,14)};
;     SBAR(); pv(o,vb0+sl_cur,PAF(0),PAF(1),PAF(2),PAF(3)); }
	v_sub_f32_e32 v63, v206, v63
	v_sub_f32_e32 v62, v206, v62
	v_pk_add_f32 v[56:57], v[82:83], v[56:57]
	v_cndmask_b32_e32 v87, v223, v40, vcc
	v_cmp_le_i32_e32 vcc, v38, v231
	v_or_b32_e32 v38, 0xc3, v228
	v_pk_add_f32 v[62:63], v[88:89], v[62:63]
	v_cndmask_b32_e32 v88, v223, v56, vcc
	v_cmp_le_i32_e32 vcc, v38, v231
	v_or_b32_e32 v38, 0xe3, v228
	v_sub_f32_e32 v43, v206, v43
	v_sub_f32_e32 v42, v206, v42
	v_sub_f32_e32 v65, v206, v65
	v_sub_f32_e32 v64, v206, v64
	v_cndmask_b32_e32 v89, v223, v41, vcc
	v_cmp_le_i32_e32 vcc, v38, v231
	v_or_b32_e32 v38, 0xc8, v228
	v_pk_add_f32 v[42:43], v[100:101], v[42:43]
	v_sub_f32_e32 v59, v206, v59
	v_sub_f32_e32 v58, v206, v58
	v_pk_add_f32 v[64:65], v[90:91], v[64:65]
	v_cndmask_b32_e32 v90, v223, v57, vcc
	v_cmp_le_i32_e32 vcc, v38, v231
	v_or_b32_e32 v38, 0xe8, v228
	v_pk_add_f32 v[58:59], v[84:85], v[58:59]
	v_cndmask_b32_e32 v54, v223, v42, vcc
	v_cmp_le_i32_e32 vcc, v38, v231
	v_or_b32_e32 v39, 0xc9, v228
	v_sub_f32_e32 v45, v206, v45
	v_cndmask_b32_e32 v38, v223, v58, vcc
	v_cmp_le_i32_e32 vcc, v39, v231
	v_or_b32_e32 v39, 0xe9, v228
	v_sub_f32_e32 v44, v206, v44
	v_cndmask_b32_e32 v55, v223, v43, vcc
	v_cmp_le_i32_e32 vcc, v39, v231
	v_or_b32_e32 v40, 0xca, v228
	v_pk_add_f32 v[44:45], v[102:103], v[44:45]
	v_cndmask_b32_e32 v39, v223, v59, vcc
	v_cmp_le_i32_e32 vcc, v40, v231
	v_or_b32_e32 v40, 0xea, v228
	v_or_b32_e32 v41, 0xcb, v228
	v_cndmask_b32_e32 v56, v223, v44, vcc
	v_cmp_le_i32_e32 vcc, v40, v231
	v_sub_f32_e32 v47, v206, v47
	v_sub_f32_e32 v46, v206, v46
	v_cndmask_b32_e32 v40, v223, v60, vcc
	v_cmp_le_i32_e32 vcc, v41, v231
	v_or_b32_e32 v41, 0xeb, v228
	v_or_b32_e32 v42, 0xd0, v228
	v_cndmask_b32_e32 v57, v223, v45, vcc
	v_cmp_le_i32_e32 vcc, v41, v231
	v_pk_add_f32 v[46:47], v[104:105], v[46:47]
	v_or_b32_e32 v43, 0xd1, v228
	v_cndmask_b32_e32 v41, v223, v61, vcc
	v_cmp_le_i32_e32 vcc, v42, v231
	v_or_b32_e32 v42, 0xf0, v228
	v_sub_f32_e32 v49, v206, v49
	v_cndmask_b32_e32 v58, v223, v46, vcc
	v_cmp_le_i32_e32 vcc, v42, v231
	v_sub_f32_e32 v48, v206, v48
	v_or_b32_e32 v44, 0xd2, v228
	v_cndmask_b32_e32 v42, v223, v62, vcc
	v_cmp_le_i32_e32 vcc, v43, v231
	v_or_b32_e32 v43, 0xf1, v228
	v_pk_add_f32 v[48:49], v[106:107], v[48:49]
	v_cndmask_b32_e32 v59, v223, v47, vcc
	v_cmp_le_i32_e32 vcc, v43, v231
	v_or_b32_e32 v45, 0xd3, v228
	v_sub_f32_e32 v51, v206, v51
	v_cndmask_b32_e32 v43, v223, v63, vcc
	v_cmp_le_i32_e32 vcc, v44, v231
	v_or_b32_e32 v44, 0xf2, v228
	v_sub_f32_e32 v50, v206, v50
	v_cndmask_b32_e32 v60, v223, v48, vcc
	v_cmp_le_i32_e32 vcc, v44, v231
	v_or_b32_e32 v46, 0xd8, v228
	v_pk_add_f32 v[50:51], v[108:109], v[50:51]
	v_cndmask_b32_e32 v44, v223, v64, vcc
	v_cmp_le_i32_e32 vcc, v45, v231
	v_or_b32_e32 v45, 0xf3, v228
	s_waitcnt lgkmcnt(0)
	v_sub_f32_e32 v99, v206, v113
	v_cndmask_b32_e32 v61, v223, v49, vcc
	v_cmp_le_i32_e32 vcc, v45, v231
	v_sub_f32_e32 v98, v206, v112
	v_pk_add_f32 v[82:83], v[92:93], v[98:99]
	v_cndmask_b32_e32 v45, v223, v65, vcc
	v_cmp_le_i32_e32 vcc, v46, v231
	v_or_b32_e32 v46, 0xf8, v228
	v_or_b32_e32 v47, 0xd9, v228
	v_cndmask_b32_e32 v62, v223, v50, vcc
	v_cmp_le_i32_e32 vcc, v46, v231
	v_sub_f32_e32 v53, v206, v53
	v_sub_f32_e32 v52, v206, v52
	v_cndmask_b32_e32 v46, v223, v82, vcc
	v_cmp_le_i32_e32 vcc, v47, v231
	v_or_b32_e32 v47, 0xf9, v228
	v_or_b32_e32 v48, 0xda, v228
	v_cndmask_b32_e32 v63, v223, v51, vcc
	v_cmp_le_i32_e32 vcc, v47, v231
	v_pk_add_f32 v[52:53], v[110:111], v[52:53]
	v_sub_f32_e32 v97, v206, v115
	v_sub_f32_e32 v96, v206, v114
	v_cndmask_b32_e32 v47, v223, v83, vcc
	v_cmp_le_i32_e32 vcc, v48, v231
	v_or_b32_e32 v48, 0xfa, v228
	v_pk_add_f32 v[84:85], v[94:95], v[96:97]
	v_cndmask_b32_e32 v64, v223, v52, vcc
	v_cmp_le_i32_e32 vcc, v48, v231
	v_or_b32_e32 v49, 0xdb, v228
	s_nop 0
	v_cndmask_b32_e32 v48, v223, v84, vcc
	v_cmp_le_i32_e32 vcc, v49, v231
	v_or_b32_e32 v49, 0xfb, v228
	s_nop 0
	v_cndmask_b32_e32 v65, v223, v53, vcc
	v_cmp_le_i32_e32 vcc, v49, v231
	s_nop 1
	v_cndmask_b32_e32 v49, v223, v85, vcc
	v_mfma_f32_32x32x16_bf16 v[0:15], v[128:131], v[176:179], v[0:15]
	v_exp_f32_e32 v50, v79
	v_exp_f32_e32 v51, v81
	v_exp_f32_e32 v52, v87
	v_exp_f32_e32 v53, v89
	v_mfma_f32_32x32x16_bf16 v[16:31], v[128:131], v[172:175], v[16:31]
	v_exp_f32_e32 v54, v54
	v_exp_f32_e32 v55, v55
	v_exp_f32_e32 v56, v56
	v_exp_f32_e32 v57, v57
	v_mfma_f32_32x32x16_bf16 v[0:15], v[136:139], v[34:37], v[0:15]
	v_exp_f32_e32 v58, v58
	v_exp_f32_e32 v59, v59
	v_exp_f32_e32 v60, v60
	v_exp_f32_e32 v61, v61
	v_mfma_f32_32x32x16_bf16 v[16:31], v[136:139], v[70:73], v[16:31]
	v_exp_f32_e32 v62, v62
	v_exp_f32_e32 v63, v63
	v_exp_f32_e32 v64, v64
	v_exp_f32_e32 v65, v65
	v_mfma_f32_32x32x16_bf16 v[0:15], v[132:135], v[120:123], v[0:15]
	v_exp_f32_e32 v34, v80
	v_exp_f32_e32 v35, v86
	v_exp_f32_e32 v36, v88
	v_exp_f32_e32 v37, v90
	v_mfma_f32_32x32x16_bf16 v[16:31], v[132:135], v[66:69], v[16:31]
	v_exp_f32_e32 v38, v38
	v_exp_f32_e32 v39, v39
	v_exp_f32_e32 v40, v40
	v_exp_f32_e32 v41, v41
	v_mfma_f32_32x32x16_bf16 v[0:15], v[140:143], v[74:77], v[0:15]
	v_exp_f32_e32 v42, v42
	v_exp_f32_e32 v43, v43
	v_exp_f32_e32 v44, v44
	v_exp_f32_e32 v45, v45
	v_mfma_f32_32x32x16_bf16 v[16:31], v[140:143], v[116:119], v[16:31]
	v_exp_f32_e32 v46, v46
	v_exp_f32_e32 v47, v47
	v_exp_f32_e32 v48, v48
	v_exp_f32_e32 v49, v49
	v_cvt_pk_bf16_f32 v66, v50, v51
	v_cvt_pk_bf16_f32 v67, v52, v53
	v_cvt_pk_bf16_f32 v68, v54, v55
	v_cvt_pk_bf16_f32 v69, v56, v57
	v_cvt_pk_bf16_f32 v70, v58, v59
	v_cvt_pk_bf16_f32 v71, v60, v61
	v_cvt_pk_bf16_f32 v72, v62, v63
	v_cvt_pk_bf16_f32 v73, v64, v65
	v_cvt_pk_bf16_f32 v74, v34, v35
	v_cvt_pk_bf16_f32 v75, v36, v37
	v_cvt_pk_bf16_f32 v76, v38, v39
	v_cvt_pk_bf16_f32 v77, v40, v41
	v_cvt_pk_bf16_f32 v80, v42, v43
	v_cvt_pk_bf16_f32 v81, v44, v45
	v_cvt_pk_bf16_f32 v82, v46, v47
	v_cvt_pk_bf16_f32 v83, v48, v49
	v_add3_u32 v33, v33, v229, s59
	ds_read_b64_tr_b16 v[84:85],v33 offset:0
	ds_read_b64_tr_b16 v[86:87],v33 offset:512
	ds_read_b64_tr_b16 v[88:89],v33 offset:1024
	ds_read_b64_tr_b16 v[90:91],v33 offset:1536
	ds_read_b64_tr_b16 v[92:93],v33 offset:2048
	ds_read_b64_tr_b16 v[94:95],v33 offset:2560
	ds_read_b64_tr_b16 v[96:97],v33 offset:3072
	ds_read_b64_tr_b16 v[98:99],v33 offset:3584
	s_waitcnt lgkmcnt(0)
; __device__ __forceinline__ int crow(int r,int hi){return (r&3)+8*(r>>2)+4*hi;}
; #define SBAR() __builtin_amdgcn_sched_barrier(0)
;   #define PKW(P,B) cvtpk_s(P[B],P[B+1])
; template<int THRL> __device__ __forceinline__ void attn_unit(int b,int h,int qb,int t0,float cqv,float mfix,const float*__restrict__ cf,float cref,unsigned*counter,const bf16*Q,const bf16*__restrict__ K,const bf16*__restrict__ V,bf16*O,const bf16*__restrict__ G,char*shm){
;     ...
;   { float sacc=pB0[0]+pB0[1]; _Pragma("unroll") for(int r=2;r<16;++r)sacc+=pB0[r]; _Pragma("unroll") for(int r=0;r<16;++r)sacc+=pB1[r]; l_reg+=sacc;
;     pw0=(u32x4){PKW(pB0,0),PKW(pB0,2),PKW(pB0,4),PKW(pB0,6)};pw1=(u32x4){PKW(pB0,8),PKW(pB0,10),PKW(pB0,12),PKW(pB0,14)};pw2=(u32x4){PKW(pB1,0),PKW(pB1,2),PKW(pB1,4),PKW(pB1,6)};pw3=(u32x4){PKW(pB1,8),PKW(pB1,10),PKW(pB1,12),PKW(pB1,14)};
;     SBAR(); pv(o,vb0+sl_cur,PAF(0),PAF(1),PAF(2),PAF(3)); }
;     ...
;   int unext_=0; if(tid==0) unext_=(int)atomicAdd(counter,1u);
;   {auto rr=__builtin_amdgcn_permlane32_swap(__float_as_uint(l_reg),__float_as_uint(l_reg),false,false);l_reg=__uint_as_float(rr[0])+__uint_as_float(rr[1]);}
;   if(hi==0)wsf[32+r32]=l_reg;asm volatile("s_waitcnt lgkmcnt(0)":::"memory");
;   float rli[16];
;   #pragma unroll
;   for(int r=0;r<16;++r)rli[r]=__builtin_amdgcn_rcpf(wsf[32+crow(r,hi)]);
;   bf16*Ow=O+(rowbase+q0+wid*QBLK)*DM+h*D;
;   { bf16*stg=(bf16*)(shm+LDS_OST)+wid*2048;
;     #pragma unroll
;     for(int r=0;r<16;++r){const int orow=crow(r,hi);
;       #pragma unroll
;       for(int d0=0;d0<2;++d0)stg[orow*64+d0*32+r32]=__float2bfloat16(o[d0][r]*rli[r]);}
; template<int THRL> __device__ __forceinline__ void fox_attn_phase(char*lds,const bf16*Q,const bf16*K,const bf16*V,bf16*O,const bf16*G,const float*__restrict__ cumf,unsigned*counter,float TH,float mfix){
;     ...
;     const int qb=NQB-1-(u&31), bh=sorted[u>>5], q0=qb*QB;
;     const float* cf=cumf+(long)bh*SEQ;
;     const float cref=cf[q0];
;     const int nb=4*qb; float e0=0.f,e1=0.f;
;     if(lane<nb) e0=cf[64*lane+63];
;     if(lane+64<nb) e1=cf[64*(lane+64)+63];
	s_nop 0
	v_mfma_f32_32x32x16_bf16 v[0:15], v[66:69], v[84:87], v[0:15]
	ds_read_b64_tr_b16 v[84:85],v33 offset:4096
	ds_read_b64_tr_b16 v[86:87],v33 offset:4608
	v_mfma_f32_32x32x16_bf16 v[0:15], v[70:73], v[88:91], v[0:15]
	ds_read_b64_tr_b16 v[88:89],v33 offset:5120
	ds_read_b64_tr_b16 v[90:91],v33 offset:5632
	v_mfma_f32_32x32x16_bf16 v[0:15], v[74:77], v[92:95], v[0:15]
	ds_read_b64_tr_b16 v[92:93],v33 offset:6144
	ds_read_b64_tr_b16 v[94:95],v33 offset:6656
	v_mfma_f32_32x32x16_bf16 v[0:15], v[80:83], v[96:99], v[0:15]
	ds_read_b64_tr_b16 v[96:97],v33 offset:7168
	ds_read_b64_tr_b16 v[98:99],v33 offset:7680
	s_waitcnt lgkmcnt(0)
	v_mfma_f32_32x32x16_bf16 v[16:31], v[66:69], v[84:87], v[16:31]
	v_cmp_eq_u32_e32 vcc, 0, v226
	v_mov_b32_e32 v33, 0
	v_mfma_f32_32x32x16_bf16 v[16:31], v[70:73], v[88:91], v[16:31]
	v_mfma_f32_32x32x16_bf16 v[16:31], v[74:77], v[92:95], v[16:31]
	v_mfma_f32_32x32x16_bf16 v[16:31], v[80:83], v[96:99], v[16:31]
	s_mov_b32 s32, 0
	v_readfirstlane_b32 s98, v216
	s_lshr_b32 s98, s98, 6
	s_cmp_lg_u32 s98, 0
	s_cbranch_scc1 .Lla1_skip
	s_waitcnt vmcnt(4)
	v_readfirstlane_b32 s98, v252
	s_cmp_gt_u32 s98, 0x3ff
	s_cbranch_scc1 .Lla1_skip
	s_lshr_b32 s100, s98, 5
	s_lshl_b32 s100, s100, 2
	s_add_i32 s100, s100, 0x1c8c0
	v_mov_b32_e32 v196, s100
	ds_read_b32 v196, v196
	s_andn2_b32 s99, 31, s98
	v_and_b32_e32 v197, 63, v216
	v_lshlrev_b32_e32 v197, 8, v197
	s_waitcnt lgkmcnt(0)
	v_readfirstlane_b32 s100, v196
	s_nop 1
	s_lshl_b32 s100, s100, 15
	s_add_u32 s100, s62, s100
	s_addc_u32 s101, s63, 0
	s_lshl_b32 s98, s99, 10
	v_mov_b32_e32 v198, s98
	global_load_dword v199, v198, s[100:101]
	global_load_dword v200, v197, s[100:101] offset:252
	v_add_u32_e32 v198, 0x4000, v197
	global_load_dword v201, v198, s[100:101] offset:252
	s_mov_b32 s32, 1
.Lla1_skip:
	v_add_f32_e32 v50, v50, v51
	v_add_f32_e32 v50, v52, v50
	v_add_f32_e32 v50, v53, v50
	v_add_f32_e32 v50, v54, v50
	v_add_f32_e32 v50, v55, v50
	v_add_f32_e32 v50, v56, v50
	v_add_f32_e32 v50, v57, v50
	v_add_f32_e32 v50, v58, v50
	v_add_f32_e32 v50, v59, v50
	v_add_f32_e32 v50, v60, v50
	v_add_f32_e32 v50, v61, v50
	v_add_f32_e32 v50, v62, v50
	v_add_f32_e32 v50, v63, v50
	v_add_f32_e32 v50, v64, v50
	v_add_f32_e32 v50, v65, v50
	v_add_f32_e32 v34, v34, v50
	v_add_f32_e32 v34, v35, v34
	v_add_f32_e32 v34, v36, v34
	v_add_f32_e32 v34, v37, v34
	v_add_f32_e32 v34, v38, v34
	v_add_f32_e32 v34, v39, v34
	v_add_f32_e32 v34, v40, v34
	v_add_f32_e32 v34, v41, v34
	v_add_f32_e32 v34, v42, v34
	v_add_f32_e32 v34, v43, v34
	v_add_f32_e32 v34, v44, v34
	v_add_f32_e32 v34, v45, v34
	v_add_f32_e32 v34, v46, v34
	v_add_f32_e32 v34, v47, v34
	v_add_f32_e32 v34, v48, v34
	v_add_f32_e32 v34, v49, v34
	v_add_f32_e32 v32, v32, v78
	v_add_f32_e32 v32, v32, v34
	s_and_b32 s4, s66, 0x3fffffc0
	s_lshl_b32 s4, s4, 2
	v_mov_b32_e32 v34, v32
	s_add_i32 s16, s4, 0
	s_nop 0
	v_permlane32_swap_b32_e32 v32, v34
	v_cmp_gt_u32_e64 s[4:5], 32, v224
	s_and_saveexec_b64 s[18:19], s[4:5]
	v_lshl_add_u32 v35, v204, 2, s16
	v_add_f32_e32 v32, v32, v34
	ds_write_b32 v35, v32 offset:49280
	s_or_b64 exec, exec, s[18:19]
	s_waitcnt lgkmcnt(0)
	v_lshl_add_u32 v32, v228, 2, s16
	ds_read_b128 v[34:37], v32 offset:49280
	ds_read_b128 v[38:41], v32 offset:49312
	s_lshl_b64 s[4:5], s[38:39], 1
	s_add_u32 s14, s12, s4
	s_addc_u32 s15, s13, s5
	s_waitcnt lgkmcnt(1)
	v_rcp_f32_e32 v42, v34
	v_rcp_f32_e32 v43, v35
	v_rcp_f32_e32 v44, v36
	v_rcp_f32_e32 v45, v37
	s_waitcnt lgkmcnt(0)
	v_rcp_f32_e32 v46, v38
	ds_read_b128 v[34:37], v32 offset:49344
	v_rcp_f32_e32 v47, v39
	v_rcp_f32_e32 v48, v40
	v_rcp_f32_e32 v49, v41
	ds_read_b128 v[38:41], v32 offset:49376
	s_lshl_b32 s16, s65, 12
	s_waitcnt lgkmcnt(1)
	v_rcp_f32_e32 v32, v34
	v_rcp_f32_e32 v34, v35
	v_rcp_f32_e32 v35, v36
	v_rcp_f32_e32 v36, v37
	s_waitcnt lgkmcnt(0)
	v_rcp_f32_e32 v37, v38
	v_rcp_f32_e32 v38, v39
	v_rcp_f32_e32 v39, v40
	v_rcp_f32_e32 v40, v41
	s_add_i32 s16, s16, 0
	v_lshlrev_b32_e32 v41, 1, v204
	v_lshlrev_b32_e32 v50, 9, v227
	v_mul_f32_e32 v0, v0, v42
	v_add3_u32 v41, s16, v41, v50
	v_cvt_pk_bf16_f32 v0, v0, s0
	ds_write_b16 v41, v0 offset:51200
	v_mul_f32_e32 v0, v16, v42
	v_cvt_pk_bf16_f32 v0, v0, s0
	ds_write_b16 v41, v0 offset:51264
	v_mul_f32_e32 v0, v1, v43
	v_cvt_pk_bf16_f32 v0, v0, s0
	ds_write_b16 v41, v0 offset:51328
	v_mul_f32_e32 v0, v17, v43
	v_cvt_pk_bf16_f32 v0, v0, s0
	ds_write_b16 v41, v0 offset:51392
	v_mul_f32_e32 v0, v2, v44
	v_cvt_pk_bf16_f32 v0, v0, s0
	ds_write_b16 v41, v0 offset:51456
	v_mul_f32_e32 v0, v18, v44
	v_cvt_pk_bf16_f32 v0, v0, s0
	ds_write_b16 v41, v0 offset:51520
	v_mul_f32_e32 v0, v3, v45
	v_cvt_pk_bf16_f32 v0, v0, s0
	ds_write_b16 v41, v0 offset:51584
	v_mul_f32_e32 v0, v19, v45
	v_cvt_pk_bf16_f32 v0, v0, s0
	ds_write_b16 v41, v0 offset:51648
	v_mul_f32_e32 v0, v4, v46
	v_cvt_pk_bf16_f32 v0, v0, s0
	ds_write_b16 v41, v0 offset:52224
	v_mul_f32_e32 v0, v20, v46
	v_cvt_pk_bf16_f32 v0, v0, s0
	ds_write_b16 v41, v0 offset:52288
	v_mul_f32_e32 v0, v5, v47
	v_cvt_pk_bf16_f32 v0, v0, s0
	ds_write_b16 v41, v0 offset:52352
	v_mul_f32_e32 v0, v21, v47
	v_cvt_pk_bf16_f32 v0, v0, s0
	ds_write_b16 v41, v0 offset:52416
	v_mul_f32_e32 v0, v6, v48
	v_cvt_pk_bf16_f32 v0, v0, s0
	ds_write_b16 v41, v0 offset:52480
	v_mul_f32_e32 v0, v22, v48
	v_cvt_pk_bf16_f32 v0, v0, s0
	ds_write_b16 v41, v0 offset:52544
	v_mul_f32_e32 v0, v7, v49
	v_cvt_pk_bf16_f32 v0, v0, s0
	ds_write_b16 v41, v0 offset:52608
	v_mul_f32_e32 v0, v23, v49
	v_cvt_pk_bf16_f32 v0, v0, s0
	ds_write_b16 v41, v0 offset:52672
	v_mul_f32_e32 v0, v8, v32
	v_cvt_pk_bf16_f32 v0, v0, s0
	ds_write_b16 v41, v0 offset:53248
	v_mul_f32_e32 v0, v24, v32
	v_cvt_pk_bf16_f32 v0, v0, s0
; __device__ __forceinline__ int crow(int r,int hi){return (r&3)+8*(r>>2)+4*hi;}
; __device__ __forceinline__ unsigned cvtpk_s(float lo,float hi){f32x2_t v={lo,hi};bf16x2_t b=__builtin_convertvector(v,bf16x2_t);return __builtin_bit_cast(unsigned,b);}
; template<int THRL> __device__ __forceinline__ void attn_unit(int b,int h,int qb,int t0,float cqv,float mfix,const float*__restrict__ cf,float cref,unsigned*counter,const bf16*Q,const bf16*__restrict__ K,const bf16*__restrict__ V,bf16*O,const bf16*__restrict__ G,char*shm){
;     ...
;     for(int r=0;r<16;++r){const int orow=crow(r,hi);
;       #pragma unroll
;       for(int d0=0;d0<2;++d0)stg[orow*64+d0*32+r32]=__float2bfloat16(o[d0][r]*rli[r]);}
;     asm volatile("s_waitcnt lgkmcnt(0)":::"memory");
;     const bf16*Gw=G+(rowbase+q0+wid*QBLK)*DM+h*D;
;     u32x4 gv4[4];
;     #pragma unroll
;     for(int i=0;i<4;++i)gv4[i]=*(const u32x4*)(Gw+(long)(i*8+(lane>>3))*DM+(lane&7)*8);
;     #pragma unroll
;     for(int i=0;i<4;++i){const int row=i*8+(lane>>3),ch=lane&7; const u32x4 v=*(const u32x4*)(stg+row*64+ch*8); const u32x4 gv=gv4[i]; u32x4 w;
;       #pragma unroll
;       for(int c=0;c<4;++c){ const float ol=__uint_as_float(v[c]<<16), oh=__uint_as_float(v[c]&0xffff0000u), gl=__uint_as_float(gv[c]<<16), gh=__uint_as_float(gv[c]&0xffff0000u);
;         const float rl=ol*gl*__builtin_amdgcn_rcpf(1.f+__expf(-gl)), rh=oh*gh*__builtin_amdgcn_rcpf(1.f+__expf(-gh)); w[c]=cvtpk_s(rl,rh); }
;       ATTN_STORE16(Ow+(long)row*DM+ch*8,w);} }
	ds_write_b16 v41, v0 offset:53312
	v_mul_f32_e32 v0, v9, v34
	v_cvt_pk_bf16_f32 v0, v0, s0
	ds_write_b16 v41, v0 offset:53376
	v_mul_f32_e32 v0, v25, v34
	v_cvt_pk_bf16_f32 v0, v0, s0
	ds_write_b16 v41, v0 offset:53440
	v_mul_f32_e32 v0, v10, v35
	v_cvt_pk_bf16_f32 v0, v0, s0
	ds_write_b16 v41, v0 offset:53504
	v_mul_f32_e32 v0, v26, v35
	v_cvt_pk_bf16_f32 v0, v0, s0
	ds_write_b16 v41, v0 offset:53568
	v_mul_f32_e32 v0, v11, v36
	v_cvt_pk_bf16_f32 v0, v0, s0
	ds_write_b16 v41, v0 offset:53632
	v_mul_f32_e32 v0, v27, v36
	v_cvt_pk_bf16_f32 v0, v0, s0
	ds_write_b16 v41, v0 offset:53696
	v_mul_f32_e32 v0, v12, v37
	v_cvt_pk_bf16_f32 v0, v0, s0
	ds_write_b16 v41, v0 offset:54272
	v_mul_f32_e32 v0, v28, v37
	v_cvt_pk_bf16_f32 v0, v0, s0
	ds_write_b16 v41, v0 offset:54336
	v_mul_f32_e32 v0, v13, v38
	v_cvt_pk_bf16_f32 v0, v0, s0
	ds_write_b16 v41, v0 offset:54400
	v_mul_f32_e32 v0, v29, v38
	v_cvt_pk_bf16_f32 v0, v0, s0
	ds_write_b16 v41, v0 offset:54464
	v_mul_f32_e32 v0, v14, v39
	v_cvt_pk_bf16_f32 v0, v0, s0
	ds_write_b16 v41, v0 offset:54528
	v_mul_f32_e32 v0, v30, v39
	v_cvt_pk_bf16_f32 v0, v0, s0
	ds_write_b16 v41, v0 offset:54592
	v_mul_f32_e32 v0, v15, v40
	v_cvt_pk_bf16_f32 v0, v0, s0
	ds_write_b16 v41, v0 offset:54656
	v_mul_f32_e32 v0, v31, v40
	s_add_u32 s4, s2, s4
	v_cvt_pk_bf16_f32 v0, v0, s0
	s_addc_u32 s5, s3, s5
	ds_write_b16 v41, v0 offset:54720
	s_add_u32 s4, s4, s52
	v_lshlrev_b32_e32 v0, 1, v225
	s_addc_u32 s5, s5, s53
	v_and_b32_e32 v204, 0x70, v0
	v_lshlrev_b32_e32 v2, 8, v224
	v_lshl_add_u64 v[0:1], s[4:5], 0, v[204:205]
	v_and_b32_e32 v2, 0x3800, v2
	v_mov_b32_e32 v3, v205
	s_waitcnt lgkmcnt(0)
	v_lshl_add_u64 v[0:1], v[0:1], 0, v[2:3]
	s_cmp_eq_u32 s32, 1
	s_cbranch_scc1 .Lgw0
	s_waitcnt vmcnt(0)
	s_branch .Lgw1
.Lgw0:
	s_waitcnt vmcnt(3)
.Lgw1:
	v_mov_b64_e32 v[14:15], v[180:181]
	v_mov_b64_e32 v[16:17], v[182:183]
	s_movk_i32 s4, 0x4000
	v_add_co_u32_e64 v2, s[4:5], s4, v0
	v_lshrrev_b32_e32 v32, 3, v224
	s_nop 0
	v_addc_co_u32_e64 v3, s[4:5], 0, v1, s[4:5]
	v_mov_b64_e32 v[8:9], v[184:185]
	v_mov_b64_e32 v[10:11], v[186:187]
	s_mov_b32 s4, 0x8000
	v_add_co_u32_e64 v2, s[4:5], s4, v0
	v_add_u32_e32 v34, s16, v204
	s_nop 0
	v_addc_co_u32_e64 v3, s[4:5], 0, v1, s[4:5]
	s_mov_b32 s4, 0xc000
	s_nop 0
	v_add_co_u32_e64 v0, s[4:5], s4, v0
	v_lshl_add_u32 v18, v32, 7, v34
	s_nop 0
	v_addc_co_u32_e64 v1, s[4:5], 0, v1, s[4:5]
	v_mov_b64_e32 v[4:5], v[188:189]
	v_mov_b64_e32 v[6:7], v[190:191]
	s_nop 0
	v_mov_b64_e32 v[0:1], v[192:193]
	v_mov_b64_e32 v[2:3], v[194:195]
	v_or_b32_e32 v35, 8, v32
	s_add_u32 s4, s14, s52
	s_addc_u32 s5, s15, s53
	v_lshl_add_u64 v[12:13], s[4:5], 0, v[204:205]
	v_lshlrev_b32_e32 v204, 11, v32
	v_lshlrev_b32_e32 v26, 16, v14
	v_and_b32_e32 v29, 0xffff0000, v14
	v_mul_f32_e32 v14, 0xbfb8aa3b, v26
	v_exp_f32_e32 v14, v14
	v_mul_f32_e32 v19, 0xbfb8aa3b, v29
	v_exp_f32_e32 v22, v19
	ds_read_b128 v[18:21], v18 offset:51200
	v_add_f32_e32 v14, 1.0, v14
	v_rcp_f32_e32 v30, v14
	v_add_f32_e32 v14, 1.0, v22
	v_rcp_f32_e32 v31, v14
	v_lshl_add_u32 v14, v35, 7, v34
	ds_read_b128 v[22:25], v14 offset:51200
	s_waitcnt lgkmcnt(1)
	v_and_b32_e32 v27, 0xffff0000, v18
	v_lshlrev_b32_e32 v28, 16, v18
	v_pk_mul_f32 v[26:27], v[28:29], v[26:27]
	v_lshlrev_b32_e32 v28, 16, v15
	v_pk_mul_f32 v[26:27], v[30:31], v[26:27]
	v_and_b32_e32 v31, 0xffff0000, v15
	v_mul_f32_e32 v14, 0xbfb8aa3b, v28
	v_exp_f32_e32 v15, v14
	v_mul_f32_e32 v14, 0xbfb8aa3b, v31
	v_exp_f32_e32 v18, v14
	v_cvt_pk_bf16_f32 v14, v26, v27
	v_add_f32_e32 v15, 1.0, v15
	v_rcp_f32_e32 v26, v15
	v_add_f32_e32 v15, 1.0, v18
	v_rcp_f32_e32 v27, v15
	v_and_b32_e32 v29, 0xffff0000, v19
	v_lshlrev_b32_e32 v30, 16, v19
	v_pk_mul_f32 v[18:19], v[30:31], v[28:29]
	v_and_b32_e32 v29, 0xffff0000, v16
	v_pk_mul_f32 v[18:19], v[26:27], v[18:19]
	v_lshlrev_b32_e32 v26, 16, v16
	v_mul_f32_e32 v15, 0xbfb8aa3b, v26
	v_exp_f32_e32 v16, v15
	v_mul_f32_e32 v15, 0xbfb8aa3b, v29
	v_exp_f32_e32 v27, v15
	v_cvt_pk_bf16_f32 v15, v18, v19
	v_add_f32_e32 v16, 1.0, v16
	v_rcp_f32_e32 v18, v16
	v_add_f32_e32 v16, 1.0, v27
	v_rcp_f32_e32 v19, v16
	v_and_b32_e32 v27, 0xffff0000, v20
	v_lshlrev_b32_e32 v28, 16, v20
	v_pk_mul_f32 v[26:27], v[28:29], v[26:27]
	v_and_b32_e32 v29, 0xffff0000, v17
	v_pk_mul_f32 v[18:19], v[18:19], v[26:27]
	v_lshlrev_b32_e32 v26, 16, v17
	v_mul_f32_e32 v16, 0xbfb8aa3b, v26
	v_exp_f32_e32 v17, v16
	v_mul_f32_e32 v16, 0xbfb8aa3b, v29
	v_exp_f32_e32 v20, v16
	v_cvt_pk_bf16_f32 v16, v18, v19
	v_add_f32_e32 v17, 1.0, v17
	v_rcp_f32_e32 v18, v17
	v_add_f32_e32 v17, 1.0, v20
	v_rcp_f32_e32 v19, v17
	v_and_b32_e32 v27, 0xffff0000, v21
	v_lshlrev_b32_e32 v28, 16, v21
	v_pk_mul_f32 v[20:21], v[28:29], v[26:27]
	v_and_b32_e32 v27, 0xffff0000, v8
	v_pk_mul_f32 v[18:19], v[18:19], v[20:21]
	v_lshlrev_b32_e32 v20, 16, v8
	v_mul_f32_e32 v8, 0xbfb8aa3b, v20
	v_exp_f32_e32 v8, v8
	v_mul_f32_e32 v21, 0xbfb8aa3b, v27
	v_exp_f32_e32 v21, v21
	v_cvt_pk_bf16_f32 v17, v18, v19
	v_lshl_add_u64 v[18:19], v[12:13], 0, v[204:205]
	v_add_f32_e32 v8, 1.0, v8
	global_store_dwordx4 v[18:19], v[14:17], off
	s_waitcnt lgkmcnt(0)
; __device__ __forceinline__ unsigned cvtpk_s(float lo,float hi){f32x2_t v={lo,hi};bf16x2_t b=__builtin_convertvector(v,bf16x2_t);return __builtin_bit_cast(unsigned,b);}
; template<int THRL> __device__ __forceinline__ void attn_unit(int b,int h,int qb,int t0,float cqv,float mfix,const float*__restrict__ cf,float cref,unsigned*counter,const bf16*Q,const bf16*__restrict__ K,const bf16*__restrict__ V,bf16*O,const bf16*__restrict__ G,char*shm){
;     ...
;     for(int i=0;i<4;++i){const int row=i*8+(lane>>3),ch=lane&7; const u32x4 v=*(const u32x4*)(stg+row*64+ch*8); const u32x4 gv=gv4[i]; u32x4 w;
;       #pragma unroll
;       for(int c=0;c<4;++c){ const float ol=__uint_as_float(v[c]<<16), oh=__uint_as_float(v[c]&0xffff0000u), gl=__uint_as_float(gv[c]<<16), gh=__uint_as_float(gv[c]&0xffff0000u);
;         const float rl=ol*gl*__builtin_amdgcn_rcpf(1.f+__expf(-gl)), rh=oh*gh*__builtin_amdgcn_rcpf(1.f+__expf(-gh)); w[c]=cvtpk_s(rl,rh); }
;       ATTN_STORE16(Ow+(long)row*DM+ch*8,w);} }
;   if(tid==0) *(volatile __attribute__((address_space(3))) int*)((__attribute__((address_space(3))) char*)shm+LDS_MISC)=unext_;
; template<int THRL> __device__ __forceinline__ void fox_attn_phase(char*lds,const bf16*Q,const bf16*K,const bf16*V,bf16*O,const bf16*G,const float*__restrict__ cumf,unsigned*counter,float TH,float mfix){
;     ...
;     { bool k0=true,k1=true;
;       if(lane<nb) k0=(cref-e0)>=-TH;
;       if(lane+64<nb) k1=(cref-e1)>=-TH;
;       const unsigned long long m0=__ballot(k0), m1=__ballot(k1);
;       int first=m0?__builtin_ctzll(m0):(m1?64+__builtin_ctzll(m1):128); if(first>nb)first=nb;
;       t0=__builtin_amdgcn_readfirstlane(first&~1); }
	v_lshlrev_b32_e32 v26, 16, v22
	v_and_b32_e32 v19, 0xffff0000, v9
	v_rcp_f32_e32 v14, v8
	v_add_f32_e32 v8, 1.0, v21
	v_rcp_f32_e32 v15, v8
	v_and_b32_e32 v21, 0xffff0000, v22
	v_pk_mul_f32 v[16:17], v[26:27], v[20:21]
	v_lshlrev_b32_e32 v18, 16, v23
	v_pk_mul_f32 v[14:15], v[14:15], v[16:17]
	v_lshlrev_b32_e32 v16, 16, v9
	v_mul_f32_e32 v8, 0xbfb8aa3b, v16
	v_exp_f32_e32 v9, v8
	v_mul_f32_e32 v8, 0xbfb8aa3b, v19
	v_exp_f32_e32 v17, v8
	v_cvt_pk_bf16_f32 v8, v14, v15
	v_add_f32_e32 v9, 1.0, v9
	v_rcp_f32_e32 v14, v9
	v_add_f32_e32 v9, 1.0, v17
	v_rcp_f32_e32 v15, v9
	v_and_b32_e32 v17, 0xffff0000, v23
	v_pk_mul_f32 v[16:17], v[18:19], v[16:17]
	v_and_b32_e32 v19, 0xffff0000, v10
	v_pk_mul_f32 v[14:15], v[14:15], v[16:17]
	v_lshlrev_b32_e32 v16, 16, v10
	v_mul_f32_e32 v9, 0xbfb8aa3b, v16
	v_exp_f32_e32 v10, v9
	v_mul_f32_e32 v9, 0xbfb8aa3b, v19
	v_exp_f32_e32 v17, v9
	v_cvt_pk_bf16_f32 v9, v14, v15
	v_add_f32_e32 v10, 1.0, v10
	v_rcp_f32_e32 v14, v10
	v_add_f32_e32 v10, 1.0, v17
	v_rcp_f32_e32 v15, v10
	v_and_b32_e32 v17, 0xffff0000, v24
	v_lshlrev_b32_e32 v18, 16, v24
	v_pk_mul_f32 v[16:17], v[18:19], v[16:17]
	v_and_b32_e32 v19, 0xffff0000, v11
	v_pk_mul_f32 v[14:15], v[14:15], v[16:17]
	v_lshlrev_b32_e32 v16, 16, v11
	v_mul_f32_e32 v10, 0xbfb8aa3b, v16
	v_exp_f32_e32 v11, v10
	v_mul_f32_e32 v10, 0xbfb8aa3b, v19
	v_exp_f32_e32 v17, v10
	v_cvt_pk_bf16_f32 v10, v14, v15
	v_add_f32_e32 v11, 1.0, v11
	v_rcp_f32_e32 v14, v11
	v_add_f32_e32 v11, 1.0, v17
	v_rcp_f32_e32 v15, v11
	v_and_b32_e32 v17, 0xffff0000, v25
	v_lshlrev_b32_e32 v18, 16, v25
	v_pk_mul_f32 v[16:17], v[18:19], v[16:17]
	v_lshlrev_b32_e32 v204, 11, v35
	v_pk_mul_f32 v[14:15], v[14:15], v[16:17]
	v_lshlrev_b32_e32 v18, 16, v4
	v_cvt_pk_bf16_f32 v11, v14, v15
	v_lshl_add_u64 v[14:15], v[12:13], 0, v[204:205]
	v_and_b32_e32 v21, 0xffff0000, v4
	v_mul_f32_e32 v4, 0xbfb8aa3b, v18
	global_store_dwordx4 v[14:15], v[8:11], off
	v_exp_f32_e32 v4, v4
	v_or_b32_e32 v24, 16, v32
	v_mul_f32_e32 v9, 0xbfb8aa3b, v21
	v_exp_f32_e32 v14, v9
	v_lshl_add_u32 v8, v24, 7, v34
	ds_read_b128 v[8:11], v8 offset:51200
	v_add_f32_e32 v4, 1.0, v4
	v_rcp_f32_e32 v22, v4
	v_add_f32_e32 v4, 1.0, v14
	v_rcp_f32_e32 v23, v4
	v_or_b32_e32 v25, 24, v32
	v_lshl_add_u32 v4, v25, 7, v34
	ds_read_b128 v[14:17], v4 offset:51200
	s_waitcnt lgkmcnt(1)
	v_and_b32_e32 v19, 0xffff0000, v8
	v_lshlrev_b32_e32 v20, 16, v8
	v_pk_mul_f32 v[18:19], v[20:21], v[18:19]
	v_lshlrev_b32_e32 v20, 16, v5
	v_pk_mul_f32 v[18:19], v[22:23], v[18:19]
	v_and_b32_e32 v23, 0xffff0000, v5
	v_mul_f32_e32 v4, 0xbfb8aa3b, v20
	v_exp_f32_e32 v5, v4
	v_mul_f32_e32 v4, 0xbfb8aa3b, v23
	v_exp_f32_e32 v8, v4
	v_cvt_pk_bf16_f32 v4, v18, v19
	v_add_f32_e32 v5, 1.0, v5
	v_rcp_f32_e32 v18, v5
	v_add_f32_e32 v5, 1.0, v8
	v_rcp_f32_e32 v19, v5
	v_and_b32_e32 v21, 0xffff0000, v9
	v_lshlrev_b32_e32 v22, 16, v9
	v_pk_mul_f32 v[8:9], v[22:23], v[20:21]
	v_and_b32_e32 v21, 0xffff0000, v6
	v_pk_mul_f32 v[8:9], v[18:19], v[8:9]
	v_lshlrev_b32_e32 v18, 16, v6
	v_mul_f32_e32 v5, 0xbfb8aa3b, v18
	v_exp_f32_e32 v6, v5
	v_mul_f32_e32 v5, 0xbfb8aa3b, v21
	v_exp_f32_e32 v19, v5
	v_cvt_pk_bf16_f32 v5, v8, v9
	v_add_f32_e32 v6, 1.0, v6
	v_rcp_f32_e32 v8, v6
	v_add_f32_e32 v6, 1.0, v19
	v_rcp_f32_e32 v9, v6
	v_and_b32_e32 v19, 0xffff0000, v10
	v_lshlrev_b32_e32 v20, 16, v10
	v_pk_mul_f32 v[18:19], v[20:21], v[18:19]
	v_and_b32_e32 v21, 0xffff0000, v7
	v_pk_mul_f32 v[8:9], v[8:9], v[18:19]
	v_lshlrev_b32_e32 v18, 16, v7
	v_mul_f32_e32 v6, 0xbfb8aa3b, v18
	v_exp_f32_e32 v7, v6
	v_mul_f32_e32 v6, 0xbfb8aa3b, v21
	v_exp_f32_e32 v10, v6
	v_cvt_pk_bf16_f32 v6, v8, v9
	v_add_f32_e32 v7, 1.0, v7
	v_rcp_f32_e32 v8, v7
	v_add_f32_e32 v7, 1.0, v10
	v_rcp_f32_e32 v9, v7
	v_and_b32_e32 v19, 0xffff0000, v11
	v_lshlrev_b32_e32 v20, 16, v11
	v_pk_mul_f32 v[10:11], v[20:21], v[18:19]
	v_and_b32_e32 v19, 0xffff0000, v0
	v_pk_mul_f32 v[8:9], v[8:9], v[10:11]
	v_lshlrev_b32_e32 v10, 16, v0
	v_mul_f32_e32 v0, 0xbfb8aa3b, v10
	v_exp_f32_e32 v0, v0
	v_mul_f32_e32 v11, 0xbfb8aa3b, v19
	v_exp_f32_e32 v11, v11
	v_lshlrev_b32_e32 v204, 11, v24
	v_cvt_pk_bf16_f32 v7, v8, v9
	v_lshl_add_u64 v[8:9], v[12:13], 0, v[204:205]
	v_add_f32_e32 v0, 1.0, v0
	global_store_dwordx4 v[8:9], v[4:7], off
	s_waitcnt lgkmcnt(0)
	v_lshlrev_b32_e32 v18, 16, v14
	v_and_b32_e32 v9, 0xffff0000, v1
	v_rcp_f32_e32 v4, v0
	v_add_f32_e32 v0, 1.0, v11
	v_rcp_f32_e32 v5, v0
	v_and_b32_e32 v11, 0xffff0000, v14
	v_pk_mul_f32 v[6:7], v[18:19], v[10:11]
	v_lshlrev_b32_e32 v8, 16, v15
	v_pk_mul_f32 v[4:5], v[4:5], v[6:7]
	v_lshlrev_b32_e32 v6, 16, v1
	v_mul_f32_e32 v0, 0xbfb8aa3b, v6
	v_exp_f32_e32 v1, v0
	v_mul_f32_e32 v0, 0xbfb8aa3b, v9
	v_exp_f32_e32 v7, v0
	v_cvt_pk_bf16_f32 v0, v4, v5
	v_add_f32_e32 v1, 1.0, v1
	v_rcp_f32_e32 v4, v1
	v_add_f32_e32 v1, 1.0, v7
	v_rcp_f32_e32 v5, v1
	v_and_b32_e32 v7, 0xffff0000, v15
	v_pk_mul_f32 v[6:7], v[8:9], v[6:7]
	v_and_b32_e32 v9, 0xffff0000, v2
	v_pk_mul_f32 v[4:5], v[4:5], v[6:7]
	v_lshlrev_b32_e32 v6, 16, v2
	v_mul_f32_e32 v1, 0xbfb8aa3b, v6
	v_exp_f32_e32 v2, v1
	v_mul_f32_e32 v1, 0xbfb8aa3b, v9
	v_exp_f32_e32 v7, v1
	v_cvt_pk_bf16_f32 v1, v4, v5
	v_add_f32_e32 v2, 1.0, v2
	v_rcp_f32_e32 v4, v2
	v_add_f32_e32 v2, 1.0, v7
	v_rcp_f32_e32 v5, v2
	v_and_b32_e32 v7, 0xffff0000, v16
	v_lshlrev_b32_e32 v8, 16, v16
	v_pk_mul_f32 v[6:7], v[8:9], v[6:7]
	v_and_b32_e32 v9, 0xffff0000, v3
	v_pk_mul_f32 v[4:5], v[4:5], v[6:7]
	v_lshlrev_b32_e32 v6, 16, v3
	v_mul_f32_e32 v2, 0xbfb8aa3b, v6
	v_exp_f32_e32 v3, v2
	v_mul_f32_e32 v2, 0xbfb8aa3b, v9
	v_exp_f32_e32 v7, v2
	v_cvt_pk_bf16_f32 v2, v4, v5
	v_add_f32_e32 v3, 1.0, v3
	v_rcp_f32_e32 v4, v3
	v_add_f32_e32 v3, 1.0, v7
	v_rcp_f32_e32 v5, v3
	v_and_b32_e32 v7, 0xffff0000, v17
	v_lshlrev_b32_e32 v8, 16, v17
	v_pk_mul_f32 v[6:7], v[8:9], v[6:7]
	v_lshlrev_b32_e32 v204, 11, v25
	v_pk_mul_f32 v[4:5], v[4:5], v[6:7]
	s_nop 0
	v_cvt_pk_bf16_f32 v3, v4, v5
	v_lshl_add_u64 v[4:5], v[12:13], 0, v[204:205]
	global_store_dwordx4 v[4:5], v[0:3], off
	s_cmp_eq_u32 s32, 1
	s_cbranch_scc0 .Lla2_skip
	s_lshl_b32 s99, s99, 2
	s_waitcnt vmcnt(4)
	v_sub_f32_e32 v200, v199, v200
	v_sub_f32_e32 v201, v199, v201
	v_and_b32_e32 v197, 63, v216
	v_cmp_ge_f32_e64 s[100:101], v200, -v218
	s_nop 1
	v_cndmask_b32_e64 v200, 0, 1, s[100:101]
	v_cmp_le_u32_e64 s[100:101], s99, v197
	s_nop 1
	v_cndmask_b32_e64 v200, v200, 1, s[100:101]
	v_cmp_ne_u32_e64 s[100:101], 0, v200
	s_nop 3
	s_ff1_i32_b64 s98, s[100:101]
	s_cmp_lg_u64 s[100:101], 0
	s_cbranch_scc1 .Lla2_have
	v_add_u32_e32 v197, 64, v197
	v_cmp_ge_f32_e64 s[100:101], v201, -v218
	s_nop 1
	v_cndmask_b32_e64 v201, 0, 1, s[100:101]
	v_cmp_le_u32_e64 s[100:101], s99, v197
	s_nop 1
	v_cndmask_b32_e64 v201, v201, 1, s[100:101]
	v_cmp_ne_u32_e64 s[100:101], 0, v201
	s_nop 3
	s_ff1_i32_b64 s98, s[100:101]
	s_or_b32 s98, s98, 64
	s_cmp_lg_u64 s[100:101], 0
	s_cselect_b32 s98, s98, 0x80
